# P4 diff_final items remapped to the XCD's own rows; P4|P5 seam now XCD-local too (6 local seams per layer)
# baseline (speedup 1.0000x reference)
; __device__ __forceinline__ const float* karg(int k) { int kk = k; asm volatile("" : "+s"(kk)); return ((const float* const __attribute__((address_space(4)))*)__builtin_amdgcn_kernarg_segment_ptr())[kk]; }
; #define PIN_TID() int tid = threadIdx.x; asm volatile("" : "+v"(tid)); const int lane = tid & 63, wid = __builtin_amdgcn_readfirstlane(tid >> 6), gw = blockIdx.x * NWAVES + wid; (void)lane; (void)gw
; #define lambda_init (0.8f - 0.6f * expf(-0.3f * (float)l))
; __device__ __forceinline__ void diff_final(const bfu* D0, const bfu* D1, float lam, const float* sg, float omli, bfu* CAT, int gw, int NGW, int lane) {
;     const int half = lane >> 5, l32 = lane & 31;
;     for (int it = gw * 2 + half; it < M * 6; it += NGW * 2) { const int row = it / 6, h = it - row * 6;
;         const v2u a_ = __builtin_nontemporal_load((const v2u*)(D0 + (size_t)row * 768 + h * 128 + l32 * 4)), b_ = __builtin_nontemporal_load((const v2u*)(D1 + (size_t)row * 768 + h * 128 + l32 * 4));
; __global__ void __launch_bounds__(NTHR, 2) fwd(Args args) {
;     ...
;         if (XEN(4) && IN_PH()) for (int rep = 0; rep < XREP(4); ++rep) { PIN_TID();
;             float lam;
;             { const float a = (lane < 64) ? karg(4)[l * 64 + lane] * karg(5)[l * 64 + lane] : 0.f, b_ = karg(6)[l * 64 + lane] * karg(7)[l * 64 + lane];
;               lam = expf(wave_sum(a)) - expf(wave_sum(b_)) + lambda_init; lam = __builtin_bit_cast(float, __builtin_amdgcn_readfirstlane(__builtin_bit_cast(int, lam))); }
;             diff_final(DIFF, DIFF1, lam, karg(8) + l * 768, 1.f - lambda_init, CAT, gw, NGW, lane);
.LBB0_498:
	s_cmp_le_i32 s58, s20
	s_cselect_b64 s[4:5], -1, 0
	s_and_b64 s[22:23], s[4:5], s[26:27]
	s_andn2_b64 vcc, exec, s[22:23]
	s_cbranch_vccnz .LBB0_503
	v_readlane_b32 s35, v255, 30
	s_mov_b32 s26, 0x3fb8aa3b
	s_mov_b32 s22, 4
	v_cvt_f32_u32_e32 v0, s35
	s_mov_b32 s27, 0xc2ce8ed0
	s_mov_b32 s34, 0x42b17218
	v_mov_b32_e32 v18, 0x7f800000
	v_mul_f32_e32 v0, 0xbe99999a, v0
	v_mul_f32_e32 v2, 0x3fb8aa3b, v0
	v_fma_f32 v3, v0, s26, -v2
	v_rndne_f32_e32 v4, v2
	v_fmac_f32_e32 v3, 0x32a5705f, v0
	v_sub_f32_e32 v2, v2, v4
	v_add_f32_e32 v2, v2, v3
	v_cvt_i32_f32_e32 v3, v4
	v_mov_b32_e32 v4, v232
	v_exp_f32_e32 v2, v2
	s_ashr_i32 s23, s22, 31
	s_lshl_b64 s[22:23], s[22:23], 3
	s_add_u32 s22, s0, s22
	s_addc_u32 s23, s1, s23
	v_ldexp_f32 v2, v2, v3
	v_cmp_ngt_f32_e32 vcc, s27, v0
	s_load_dwordx2 s[22:23], s[22:23], 0x0
	v_and_b32_e32 v3, 63, v4
	v_cndmask_b32_e32 v2, 0, v2, vcc
	v_cmp_nlt_f32_e32 vcc, s34, v0
	v_mov_b32_e32 v0, 0x3f4ccccd
	v_and_b32_e32 v5, 64, v240
	v_cndmask_b32_e32 v2, v18, v2, vcc
	v_fmamk_f32 v10, v2, 0xbf19999a, v0
	v_lshl_or_b32 v0, s35, 6, v3
	v_lshlrev_b64 v[6:7], 2, v[0:1]
	s_waitcnt lgkmcnt(0)
	v_lshl_add_u64 v[8:9], s[22:23], 0, v[6:7]
	s_mov_b32 s22, 5
	global_load_dword v0, v[8:9], off
	s_ashr_i32 s23, s22, 31
	s_lshl_b64 s[22:23], s[22:23], 3
	s_add_u32 s22, s0, s22
	s_addc_u32 s23, s1, s23
	s_load_dwordx2 s[22:23], s[22:23], 0x0
	v_add_u32_e32 v16, 64, v5
	v_xor_b32_e32 v5, 1, v240
	v_cmp_lt_i32_e32 vcc, v5, v16
	v_readfirstlane_b32 s20, v4
	s_waitcnt lgkmcnt(0)
	v_lshl_add_u64 v[8:9], s[22:23], 0, v[6:7]
	global_load_dword v11, v[8:9], off
	s_mov_b32 s22, 6
	s_ashr_i32 s23, s22, 31
	s_lshl_b64 s[22:23], s[22:23], 3
	s_add_u32 s22, s0, s22
	s_addc_u32 s23, s1, s23
	s_load_dwordx2 s[22:23], s[22:23], 0x0
	v_cndmask_b32_e32 v5, v240, v5, vcc
	v_lshlrev_b32_e32 v5, 2, v5
	s_mov_b32 s40, 21
	s_mov_b32 s38, 21
	s_waitcnt lgkmcnt(0)
	v_lshl_add_u64 v[8:9], s[22:23], 0, v[6:7]
	s_mov_b32 s22, 7
	global_load_dword v13, v[8:9], off
	s_ashr_i32 s23, s22, 31
	s_lshl_b64 s[22:23], s[22:23], 3
	s_add_u32 s22, s0, s22
	s_addc_u32 s23, s1, s23
	s_load_dwordx2 s[22:23], s[22:23], 0x0
	s_ashr_i32 s20, s20, 5
	s_and_b32 s20, s20, -2
	s_mov_b32 s36, 21
	s_waitcnt lgkmcnt(0)
	v_lshl_add_u64 v[6:7], s[22:23], 0, v[6:7]
	global_load_dword v14, v[6:7], off
	s_and_b32 s22, s2, 7
	s_mulk_i32 s22, 0x3000
	s_lshr_b32 s23, s2, 3
	s_lshl_b32 s23, s23, 4
	s_add_i32 s22, s22, s23
	s_add_i32 s20, s20, s22
	s_waitcnt vmcnt(0)
	v_mul_f32_e32 v12, v0, v11
	ds_bpermute_b32 v7, v5, v12
	s_waitcnt lgkmcnt(0)
	v_fmac_f32_e32 v7, v0, v11
	v_xor_b32_e32 v0, 2, v240
	v_cmp_lt_i32_e32 vcc, v0, v16
	s_waitcnt vmcnt(0)
	v_mul_f32_e32 v15, v13, v14
	v_cndmask_b32_e32 v0, v240, v0, vcc
	v_lshlrev_b32_e32 v6, 2, v0
	ds_bpermute_b32 v0, v6, v7
	s_waitcnt lgkmcnt(0)
	v_add_f32_e32 v0, v7, v0
	v_xor_b32_e32 v7, 4, v240
	v_cmp_lt_i32_e32 vcc, v7, v16
	s_nop 1
	v_cndmask_b32_e32 v7, v240, v7, vcc
	v_lshlrev_b32_e32 v7, 2, v7
	ds_bpermute_b32 v8, v7, v0
	s_waitcnt lgkmcnt(0)
	v_add_f32_e32 v0, v0, v8
	v_xor_b32_e32 v8, 8, v240
	v_cmp_lt_i32_e32 vcc, v8, v16
	s_nop 1
	v_cndmask_b32_e32 v8, v240, v8, vcc
	v_lshlrev_b32_e32 v8, 2, v8
	ds_bpermute_b32 v9, v8, v0
	s_waitcnt lgkmcnt(0)
	v_add_f32_e32 v0, v0, v9
	v_xor_b32_e32 v9, 16, v240
	v_cmp_lt_i32_e32 vcc, v9, v16
	s_nop 1
	v_cndmask_b32_e32 v9, v240, v9, vcc
	v_lshlrev_b32_e32 v9, 2, v9
	ds_bpermute_b32 v11, v9, v0
	s_waitcnt lgkmcnt(0)
	v_add_f32_e32 v0, v0, v11
	v_xor_b32_e32 v11, 32, v240
	v_cmp_lt_i32_e32 vcc, v11, v16
	s_nop 1
	v_cndmask_b32_e32 v11, v240, v11, vcc
	v_lshlrev_b32_e32 v11, 2, v11
	ds_bpermute_b32 v12, v11, v0
	s_waitcnt lgkmcnt(0)
	v_add_f32_e32 v0, v0, v12
	v_mul_f32_e32 v12, 0x3fb8aa3b, v0
	v_fma_f32 v16, v0, s26, -v12
	v_rndne_f32_e32 v17, v12
	v_fmac_f32_e32 v16, 0x32a5705f, v0
	v_sub_f32_e32 v12, v12, v17
	v_add_f32_e32 v12, v12, v16
	v_exp_f32_e32 v12, v12
	v_cvt_i32_f32_e32 v16, v17
	v_cmp_ngt_f32_e32 vcc, s27, v0
	v_ldexp_f32 v12, v12, v16
	s_nop 0
	v_cndmask_b32_e32 v12, 0, v12, vcc
	v_cmp_nlt_f32_e32 vcc, s34, v0
	s_nop 1
	v_cndmask_b32_e32 v0, v18, v12, vcc
	ds_bpermute_b32 v12, v5, v15
	s_waitcnt lgkmcnt(0)
	v_fmac_f32_e32 v12, v13, v14
	ds_bpermute_b32 v13, v6, v12
	s_waitcnt lgkmcnt(0)
	v_add_f32_e32 v12, v12, v13
	ds_bpermute_b32 v13, v7, v12
	s_waitcnt lgkmcnt(0)
	v_add_f32_e32 v12, v12, v13
	ds_bpermute_b32 v13, v8, v12
	s_waitcnt lgkmcnt(0)
	v_add_f32_e32 v12, v12, v13
	ds_bpermute_b32 v13, v9, v12
	s_waitcnt lgkmcnt(0)
	v_add_f32_e32 v12, v12, v13
	ds_bpermute_b32 v11, v11, v12
	s_waitcnt lgkmcnt(0)
	v_add_f32_e32 v11, v12, v11
	v_mul_f32_e32 v12, 0x3fb8aa3b, v11
	v_fma_f32 v13, v11, s26, -v12
	v_rndne_f32_e32 v14, v12
	v_fmac_f32_e32 v13, 0x32a5705f, v11
	v_sub_f32_e32 v12, v12, v14
	v_add_f32_e32 v12, v12, v13
	v_exp_f32_e32 v12, v12
	v_cvt_i32_f32_e32 v13, v14
	v_cmp_ngt_f32_e32 vcc, s27, v11
	v_ldexp_f32 v12, v12, v13
	s_nop 0
	v_cndmask_b32_e32 v12, 0, v12, vcc
	v_cmp_nlt_f32_e32 vcc, s34, v11
	s_mov_b32 s34, 8
	s_nop 0
	v_cndmask_b32_e32 v11, v18, v12, vcc
	v_sub_f32_e32 v0, v0, v11
	v_add_f32_e32 v0, v10, v0
	s_nop 0
	v_readfirstlane_b32 s26, v0
	v_bfe_u32 v0, v4, 5, 1
	v_or_b32_e32 v10, s20, v0
	s_mov_b32 s20, 0x18000
	v_cmp_gt_i32_e32 vcc, s20, v10
	s_and_saveexec_b64 s[42:43], vcc
	s_cbranch_execz .LBB0_502
	s_ashr_i32 s41, s40, 31
	s_lshl_b64 s[22:23], s[40:41], 3
	s_add_u32 s22, s0, s22
	s_addc_u32 s23, s1, s23
	s_load_dwordx2 s[22:23], s[22:23], 0x0
	v_mul_f32_e32 v0, 0x3f19999a, v2
	v_readlane_b32 s20, v255, 30
	s_mulk_i32 s20, 0x300
	v_add_f32_e32 v0, 0xbf4ccccd, v0
	s_waitcnt lgkmcnt(0)
	s_add_u32 s40, s22, 0x2d600000
	s_addc_u32 s41, s23, 0
	s_ashr_i32 s39, s38, 31
	s_lshl_b64 s[22:23], s[38:39], 3
	s_add_u32 s22, s0, s22
	s_addc_u32 s23, s1, s23
	s_load_dwordx2 s[22:23], s[22:23], 0x0
	v_add_f32_e32 v11, 1.0, v0
	v_lshlrev_b32_e32 v0, 2, v3
	v_and_b32_e32 v12, 0x7c, v0
	v_lshlrev_b32_e32 v0, 2, v12
	s_waitcnt lgkmcnt(0)
	s_add_u32 s44, s22, 0x35600000
	s_addc_u32 s45, s23, 0
	s_ashr_i32 s35, s34, 31
	s_lshl_b64 s[22:23], s[34:35], 3
	s_add_u32 s22, s0, s22
	s_addc_u32 s23, s1, s23
	s_ashr_i32 s37, s36, 31
	s_load_dwordx2 s[22:23], s[22:23], 0x0
	s_lshl_b64 s[34:35], s[36:37], 3
	s_add_u32 s34, s0, s34
	s_addc_u32 s35, s1, s35
	s_load_dwordx2 s[34:35], s[34:35], 0x0
	s_lshl_b64 s[36:37], s[20:21], 2
	s_waitcnt lgkmcnt(0)
	s_add_u32 s22, s22, s36
	s_addc_u32 s23, s23, s37
	s_mov_b32 s27, s26
	s_mov_b32 s20, s26
	v_lshl_add_u64 v[2:3], s[22:23], 0, v[0:1]
	v_lshlrev_b32_e32 v4, 7, v10
	s_mov_b64 s[36:37], 0
	v_lshlrev_b32_e32 v0, 1, v12
	s_xor_b32 s46, s26, 0x80000000
; __device__ __forceinline__ unsigned pk2(float lo, float hi) { return pg8::cvt_pk_bf16(lo, hi); }
; __device__ __forceinline__ void diff_final(const bfu* D0, const bfu* D1, float lam, const float* sg, float omli, bfu* CAT, int gw, int NGW, int lane) {
;     const int half = lane >> 5, l32 = lane & 31;
;     for (int it = gw * 2 + half; it < M * 6; it += NGW * 2) { const int row = it / 6, h = it - row * 6;
;         const v2u a_ = __builtin_nontemporal_load((const v2u*)(D0 + (size_t)row * 768 + h * 128 + l32 * 4)), b_ = __builtin_nontemporal_load((const v2u*)(D1 + (size_t)row * 768 + h * 128 + l32 * 4));
;         const f32x4 v = (f32x4){bflo(a_.x), bfhi(a_.x), bflo(a_.y), bfhi(a_.y)} - (f32x4){bflo(b_.x), bfhi(b_.x), bflo(b_.y), bfhi(b_.y)} * lam; float s = (v.x * v.x + v.y * v.y) + (v.z * v.z + v.w * v.w);
; #pragma unroll
;         for (int o = 1; o < 32; o <<= 1) s += __shfl_xor(s, o);
;         const float r = omli / sqrtf(s * (1.f / 128.f) + EPS); const f32x4 g4 = *(const f32x4*)(sg + h * 128 + l32 * 4);
;         v2u w; w.x = pk2(v.x * r * g4.x, v.y * r * g4.y); w.y = pk2(v.z * r * g4.z, v.w * r * g4.w); *(v2u*)(CAT + (size_t)row * DM + 768 + h * 128 + l32 * 4) = w; }
; }
.LBB0_501:
	s_mov_b32 s22, 0x2aaaaaab
	v_mul_hi_i32 v16, v10, s22
	v_lshrrev_b32_e32 v17, 31, v16
	v_mov_b64_e32 v[12:13], s[40:41]
	v_add_u32_e32 v16, v16, v17
	v_mad_i64_i32 v[12:13], s[22:23], v16, s66, v[12:13]
	s_movk_i32 s22, 0xfd00
	s_nop 0
	v_mad_u64_u32 v[18:19], s[22:23], v16, s22, v[4:5]
	v_ashrrev_i32_e32 v19, 31, v18
	v_mov_b64_e32 v[14:15], s[44:45]
	v_lshlrev_b64 v[20:21], 1, v[18:19]
	v_mad_i64_i32 v[14:15], s[22:23], v16, s66, v[14:15]
	v_lshl_add_u64 v[12:13], v[12:13], 0, v[20:21]
	v_lshl_add_u64 v[14:15], v[14:15], 0, v[20:21]
	v_lshl_add_u64 v[12:13], v[12:13], 0, v[0:1]
	v_lshl_add_u64 v[14:15], v[14:15], 0, v[0:1]
	global_load_dwordx2 v[22:23], v[12:13], off nt
	global_load_dwordx2 v[24:25], v[14:15], off nt
	v_ashrrev_i32_e32 v17, 31, v16
	v_lshlrev_b64 v[12:13], 12, v[16:17]
	v_lshl_add_u64 v[14:15], v[18:19], 2, v[2:3]
	v_lshl_add_u64 v[16:17], s[34:35], 0, v[12:13]
	global_load_dwordx4 v[12:15], v[14:15], off
	s_xor_b32 s47, s20, 0x80000000
	v_lshl_add_u64 v[16:17], v[16:17], 0, v[20:21]
	v_add_u32_e32 v10, 0x200, v10
	s_and_b32 s22, s2, 7
	s_mulk_i32 s22, 0x3000
	s_addk_i32 s22, 0x2fff
	v_cmp_lt_i32_e32 vcc, s22, v10
	s_or_b64 s[36:37], vcc, s[36:37]
	v_lshl_add_u64 v[16:17], v[16:17], 0, v[0:1]
	v_add_u32_e32 v4, 0x10000, v4
	s_waitcnt vmcnt(2)
	v_lshlrev_b32_e32 v18, 16, v22
	v_and_b32_e32 v19, 0xffff0000, v22
	v_lshlrev_b32_e32 v20, 16, v23
	v_and_b32_e32 v21, 0xffff0000, v23
	s_waitcnt vmcnt(1)
	v_lshlrev_b32_e32 v22, 16, v24
	v_and_b32_e32 v23, 0xffff0000, v24
	v_lshlrev_b32_e32 v24, 16, v25
	v_and_b32_e32 v25, 0xffff0000, v25
	v_pk_fma_f32 v[18:19], s[26:27], v[22:23], v[18:19] neg_lo:[1,0,0] neg_hi:[1,0,0]
	v_pk_fma_f32 v[20:21], s[46:47], v[24:25], v[20:21]
	v_pk_mul_f32 v[24:25], v[18:19], v[18:19]
	v_pk_mul_f32 v[22:23], v[20:21], v[20:21]
	s_nop 0
	v_pk_mov_b32 v[26:27], v[24:25], v[22:23] op_sel:[1,0]
	v_mov_b32_e32 v25, v23
	v_pk_add_f32 v[22:23], v[26:27], v[24:25]
	s_nop 0
	v_add_f32_e32 v22, v22, v23
	s_waitcnt lgkmcnt(0)
	s_nop 1
	v_add_f32_dpp v22, v22, v22 quad_perm:[1,0,3,2] row_mask:0xf bank_mask:0xf
	s_nop 1
	v_add_f32_dpp v22, v22, v22 quad_perm:[2,3,0,1] row_mask:0xf bank_mask:0xf
	s_nop 1
	v_add_f32_dpp v22, v22, v22 row_half_mirror row_mask:0xf bank_mask:0xf
	s_nop 1
	v_add_f32_dpp v22, v22, v22 row_mirror row_mask:0xf bank_mask:0xf
	v_mov_b32_e32 v23, v22
	s_nop 1
	v_permlane16_swap_b32_e32 v22, v23
	v_add_f32_e32 v22, v22, v23
	v_fmamk_f32 v22, v22, 0x3c000000, v236
	v_mul_f32_e32 v23, 0x4f800000, v22
	v_cmp_gt_f32_e32 vcc, s68, v22
	s_nop 1
	v_cndmask_b32_e32 v22, v22, v23, vcc
	v_sqrt_f32_e32 v23, v22
	s_nop 0
	v_add_u32_e32 v24, -1, v23
	v_add_u32_e32 v25, 1, v23
	v_fma_f32 v26, -v24, v23, v22
	v_fma_f32 v27, -v25, v23, v22
	v_cmp_ge_f32_e64 s[38:39], 0, v26
	s_nop 1
	v_cndmask_b32_e64 v23, v23, v24, s[38:39]
	v_cmp_lt_f32_e64 s[38:39], 0, v27
	s_nop 1
	v_cndmask_b32_e64 v23, v23, v25, s[38:39]
	v_mul_f32_e32 v24, 0x37800000, v23
	v_cndmask_b32_e32 v23, v23, v24, vcc
	v_cmp_class_f32_e32 vcc, v22, v234
	s_nop 1
	v_cndmask_b32_e32 v22, v23, v22, vcc
	v_div_scale_f32 v23, s[22:23], v22, v22, v11
	v_rcp_f32_e32 v25, v23
	v_div_scale_f32 v24, vcc, v11, v22, v11
	v_fma_f32 v26, -v23, v25, 1.0
	v_fmac_f32_e32 v25, v26, v25
	v_mul_f32_e32 v26, v24, v25
	v_fma_f32 v27, -v23, v26, v24
	v_fmac_f32_e32 v26, v27, v25
	v_fma_f32 v23, -v23, v26, v24
	v_div_fmas_f32 v23, v23, v25, v26
	v_div_fixup_f32 v22, v23, v22, v11
	v_pk_mul_f32 v[18:19], v[18:19], v[22:23] op_sel_hi:[1,0]
	v_pk_mul_f32 v[20:21], v[20:21], v[22:23] op_sel_hi:[1,0]
	v_add_co_u32_e32 v16, vcc, 0x29600000, v16
	s_waitcnt vmcnt(0)
	v_pk_mul_f32 v[12:13], v[12:13], v[18:19]
	v_pk_mul_f32 v[14:15], v[14:15], v[20:21]
	v_addc_co_u32_e32 v17, vcc, 0, v17, vcc
	v_cvt_pk_bf16_f32 v12, v12, v13
	v_cvt_pk_bf16_f32 v13, v14, v15
	global_store_dwordx2 v[16:17], v[12:13], off offset:1536
	s_andn2_b64 exec, exec, s[36:37]
	s_cbranch_execnz .LBB0_501

; __device__ __forceinline__ unsigned xb_ld(unsigned* p)              { return __hip_atomic_load(p, __ATOMIC_RELAXED, __HIP_MEMORY_SCOPE_AGENT); }
; __device__ __forceinline__ unsigned xb_add(unsigned* p, unsigned v) { return __hip_atomic_fetch_add(p, v, __ATOMIC_RELAXED, __HIP_MEMORY_SCOPE_AGENT); }
; #define XB_SPIN(cond, bar) do { unsigned _sp = 0; while (cond) { __builtin_amdgcn_s_sleep(1); \
;     if ((++_sp & 255u) == 0u) { if (xb_ld(&(bar)[XB_TMO])) break; if (_sp > XB_SPIN_CAP) { atomicAdd(&(bar)[XB_TMO], 1u); break; } } } } while (0)
; __device__ __forceinline__ void xcd_barrier(const XcdBarrier& b) {
;     asm volatile("s_waitcnt vmcnt(0)" ::: "memory");
;     __syncthreads();
;     if (threadIdx.x == 0) {
;         unsigned* bar = b.bar;
;         __builtin_amdgcn_s_waitcnt(0);
;         unsigned nloc = b.st[0], nx = b.st[1];
;         if (nloc == 0u) { xcd_barrier_complete(bar, b.x, nloc, nx); b.st[0] = nloc; b.st[1] = nx; }
;         const unsigned old = xb_add(&bar[XB_XSUB(b.x)], 1u);
;         const unsigned gen = old / nloc;
;         if (old + 1u == (gen + 1u) * nloc) {
;             __builtin_amdgcn_fence(__ATOMIC_RELEASE, "agent");
;             asm volatile("s_waitcnt vmcnt(0)" ::: "memory");
;             const unsigned og = xb_add(&bar[XB_TOP], 1u);
;             const unsigned tg = og / nx;
;             if (og + 1u == (tg + 1u) * nx) xb_add(&bar[XB_TOPGEN], 1u);
;             else XB_SPIN(xb_ld(&bar[XB_TOPGEN]) == tg, bar);
;             __builtin_amdgcn_fence(__ATOMIC_ACQUIRE, "agent");
;             xb_add(&bar[XB_XGEN(b.x)], 1u);
;             asm volatile("s_waitcnt vmcnt(0)" ::: "memory");
;         } else {
;             XB_SPIN(xb_ld(&bar[XB_XGEN(b.x)]) == gen, bar);
;             __builtin_amdgcn_fence(__ATOMIC_ACQUIRE, "agent");
;             asm volatile("s_waitcnt vmcnt(0)" ::: "memory");
;         }
.Llseam_known_15527:
	s_cmp_eq_u32 s100, 1
	s_cbranch_scc1 .LBB0_553
	buffer_wbl2 sc1
	s_waitcnt lgkmcnt(0)
	s_waitcnt vmcnt(0)
	v_mbcnt_lo_u32_b32 v0, s34, 0
	v_mbcnt_hi_u32_b32 v0, s35, v0
	v_cmp_eq_u32_e32 vcc, 0, v0
	s_and_saveexec_b64 s[36:37], vcc
	s_cbranch_execz .LBB0_539
	s_bcnt1_i32_b64 s22, s[34:35]
	v_mov_b32_e32 v3, s22
	v_readlane_b32 s22, v255, 6
	v_readlane_b32 s23, v255, 7
	s_nop 4
	global_atomic_add v3, v1, v3, s[22:23] sc0
.LBB0_539:
	s_or_b64 exec, exec, s[36:37]
	s_waitcnt vmcnt(0)
	v_readfirstlane_b32 s22, v3
	v_sub_u32_e32 v4, 0, v2
	s_mov_b64 s[36:37], -1
	v_add_u32_e32 v3, s22, v0
	v_cvt_f32_u32_e32 v0, v2
	v_readlane_b32 s22, v255, 8
	v_readlane_b32 s23, v255, 9
	v_rcp_iflag_f32_e32 v0, v0
	s_nop 0
	v_mul_f32_e32 v0, 0x4f7ffffe, v0
	v_cvt_u32_f32_e32 v0, v0
	v_mul_lo_u32 v4, v4, v0
	v_mul_hi_u32 v4, v0, v4
	v_add_u32_e32 v0, v0, v4
	v_mul_hi_u32 v0, v3, v0
	v_mul_lo_u32 v4, v0, v2
	v_sub_u32_e32 v4, v3, v4
	v_cmp_ge_u32_e32 vcc, v4, v2
	v_add_u32_e32 v5, 1, v0
	v_add_u32_e32 v3, 1, v3
	v_cndmask_b32_e32 v0, v0, v5, vcc
	v_sub_u32_e32 v5, v4, v2
	v_cndmask_b32_e32 v4, v4, v5, vcc
	v_cmp_ge_u32_e32 vcc, v4, v2
	v_add_u32_e32 v4, 1, v0
	s_nop 0
	v_cndmask_b32_e32 v0, v0, v4, vcc
	v_mul_lo_u32 v4, v2, v0
	v_add_u32_e32 v2, v4, v2
	v_cmp_ne_u32_e32 vcc, v3, v2
	v_mov_b64_e32 v[2:3], s[22:23]
	s_and_saveexec_b64 s[34:35], vcc
	s_cbranch_execz .LBB0_551
	v_readlane_b32 s22, v255, 8
	v_readlane_b32 s23, v255, 9
	s_mov_b64 s[38:39], 0
	s_nop 3
	global_load_dword v2, v1, s[22:23] sc1
	s_waitcnt vmcnt(0)
	v_cmp_eq_u32_e32 vcc, v2, v0
	s_and_saveexec_b64 s[36:37], vcc
	s_cbranch_execz .LBB0_550
	s_mov_b32 s22, 1
	s_branch .LBB0_543
